# SwiGLU epilogue math re-emitted per 16-row group: batched exp/rcp, row scale folded into the exponent constant, no dependent-chain nops (f32 throughout)
# baseline (speedup 1.0000x reference)
; __device__ __forceinline__ unsigned cvt_pk_bf16(float lo, float hi) { f32x2 v = {lo, hi}; bf16x2_t b = __builtin_convertvector(v, bf16x2_t); return __builtin_bit_cast(unsigned, b); }
; __device__ __forceinline__ float ssq_rs(const ssq_t* p, float inv_k) { return __builtin_amdgcn_rsqf((float)(*p) * (inv_k * SSQ_INV) + RMS_EPS); }
;     __device__ __forceinline__ void operator()(const f32x4 (&acc)[2][2][4][2], const Unit& u, int wr, int wc, int fr, int fq) const {
;     ...
;         for (int ai = 0; ai < 2; ++ai)
; #pragma unroll
;             for (int m = 0; m < 4; ++m) {
;                 const int row = row0 + ai * HALF + m * 16;
;                 const float rs = ssq_rs(ss + row, inv_k);
;                 float hv[8];
; #pragma unroll
;                 for (int j = 0; j < 8; ++j) {
;                     const float gt = acc[ai][0][m][j >> 2][j & 3] * rs, up = acc[ai][1][m][j >> 2][j & 3] * rs;
;                     hv[j] = gt * __builtin_amdgcn_rcpf(1.f + __builtin_amdgcn_exp2f(-1.4426950408889634f * gt)) * up;
;                 }
;                 u32x4 w; w.x = cvt_pk_bf16(hv[0], hv[1]); w.y = cvt_pk_bf16(hv[2], hv[3]); w.z = cvt_pk_bf16(hv[4], hv[5]); w.w = cvt_pk_bf16(hv[6], hv[7]);
;                 *(u32x4*)(O + (size_t)row * ldc + col0) = w;
;             }
.LBB0_275:
	s_and_b64 vcc, exec, s[50:51]
	s_cbranch_vccz .LBB0_277
	v_ashrrev_i32_e32 v225, 31, v224
	v_lshl_add_u64 v[136:137], v[224:225], 2, v[208:209]
	flat_load_dword v130, v[136:137]
	v_lshl_or_b32 v134, s22, 7, v241
	v_ashrrev_i32_e32 v135, 31, v134
	v_lshlrev_b64 v[134:135], 1, v[134:135]
	s_waitcnt vmcnt(0) lgkmcnt(0)
	v_cvt_f32_u32_e32 v130, v130
	v_fmaak_f32 v130, v250, v130, 0x358637bd
	v_rsq_f32_e32 v130, v130
	s_nop 0
	v_mul_f32_e32 v164, v130, v130
	v_mul_f32_e32 v131, 0xbfb8aa3b, v130
	v_mul_f32_e32 v156, v131, v126
	v_mul_f32_e32 v157, v131, v127
	v_mul_f32_e32 v158, v131, v128
	v_mul_f32_e32 v159, v131, v129
	v_mul_f32_e32 v160, v131, v122
	v_mul_f32_e32 v161, v131, v123
	v_mul_f32_e32 v162, v131, v124
	v_mul_f32_e32 v163, v131, v125
	v_exp_f32_e32 v156, v156
	v_exp_f32_e32 v157, v157
	v_exp_f32_e32 v158, v158
	v_exp_f32_e32 v159, v159
	v_exp_f32_e32 v160, v160
	v_exp_f32_e32 v161, v161
	v_exp_f32_e32 v162, v162
	v_exp_f32_e32 v163, v163
	v_add_f32_e32 v156, 1.0, v156
	v_add_f32_e32 v157, 1.0, v157
	v_add_f32_e32 v158, 1.0, v158
	v_add_f32_e32 v159, 1.0, v159
	v_add_f32_e32 v160, 1.0, v160
	v_add_f32_e32 v161, 1.0, v161
	v_add_f32_e32 v162, 1.0, v162
	v_add_f32_e32 v163, 1.0, v163
	v_rcp_f32_e32 v156, v156
	v_rcp_f32_e32 v157, v157
	v_rcp_f32_e32 v158, v158
	v_rcp_f32_e32 v159, v159
	v_rcp_f32_e32 v160, v160
	v_rcp_f32_e32 v161, v161
	v_rcp_f32_e32 v162, v162
	v_rcp_f32_e32 v163, v163
	v_pk_mul_f32 v[126:127], v[126:127], v[118:119]
	v_pk_mul_f32 v[128:129], v[128:129], v[120:121]
	v_pk_mul_f32 v[122:123], v[122:123], v[114:115]
	v_pk_mul_f32 v[124:125], v[124:125], v[116:117]
	v_pk_mul_f32 v[126:127], v[126:127], v[164:165] op_sel_hi:[1,0]
	v_pk_mul_f32 v[128:129], v[128:129], v[164:165] op_sel_hi:[1,0]
	v_pk_mul_f32 v[122:123], v[122:123], v[164:165] op_sel_hi:[1,0]
	v_pk_mul_f32 v[124:125], v[124:125], v[164:165] op_sel_hi:[1,0]
	v_pk_mul_f32 v[126:127], v[126:127], v[156:157]
	v_pk_mul_f32 v[128:129], v[128:129], v[158:159]
	v_pk_mul_f32 v[122:123], v[122:123], v[160:161]
	v_pk_mul_f32 v[124:125], v[124:125], v[162:163]
	v_cvt_pk_bf16_f32 v130, v126, v127
	v_cvt_pk_bf16_f32 v131, v128, v129
	v_cvt_pk_bf16_f32 v132, v122, v123
	v_cvt_pk_bf16_f32 v133, v124, v125
	v_mul_lo_u32 v139, s67, v224
	v_mul_lo_u32 v138, s66, v225
	v_mad_u64_u32 v[140:141], s[50:51], s66, v224, 0
	v_add3_u32 v141, v141, v138, v139
	v_lshl_add_u64 v[140:141], v[140:141], 1, s[68:69]
	v_lshl_add_u64 v[140:141], v[140:141], 0, v[134:135]
	flat_store_dwordx4 v[140:141], v[130:133]
	flat_load_dword v130, v[136:137] offset:64
	v_or_b32_e32 v139, 16, v224
	s_waitcnt vmcnt(0) lgkmcnt(0)
	v_cvt_f32_u32_e32 v130, v130
	v_fmaak_f32 v130, v250, v130, 0x358637bd
	v_rsq_f32_e32 v130, v130
	s_nop 0
	v_mul_f32_e32 v164, v130, v130
	v_mul_f32_e32 v131, 0xbfb8aa3b, v130
	v_mul_f32_e32 v156, v131, v110
	v_mul_f32_e32 v157, v131, v111
	v_mul_f32_e32 v158, v131, v112
	v_mul_f32_e32 v159, v131, v113
	v_mul_f32_e32 v160, v131, v106
	v_mul_f32_e32 v161, v131, v107
	v_mul_f32_e32 v162, v131, v108
	v_mul_f32_e32 v163, v131, v109
	v_exp_f32_e32 v156, v156
	v_exp_f32_e32 v157, v157
	v_exp_f32_e32 v158, v158
	v_exp_f32_e32 v159, v159
	v_exp_f32_e32 v160, v160
	v_exp_f32_e32 v161, v161
	v_exp_f32_e32 v162, v162
	v_exp_f32_e32 v163, v163
	v_add_f32_e32 v156, 1.0, v156
	v_add_f32_e32 v157, 1.0, v157
	v_add_f32_e32 v158, 1.0, v158
	v_add_f32_e32 v159, 1.0, v159
	v_add_f32_e32 v160, 1.0, v160
	v_add_f32_e32 v161, 1.0, v161
	v_add_f32_e32 v162, 1.0, v162
	v_add_f32_e32 v163, 1.0, v163
	v_rcp_f32_e32 v156, v156
	v_rcp_f32_e32 v157, v157
	v_rcp_f32_e32 v158, v158
	v_rcp_f32_e32 v159, v159
	v_rcp_f32_e32 v160, v160
	v_rcp_f32_e32 v161, v161
	v_rcp_f32_e32 v162, v162
	v_rcp_f32_e32 v163, v163
	v_pk_mul_f32 v[110:111], v[110:111], v[102:103]
	v_pk_mul_f32 v[112:113], v[112:113], v[104:105]
	v_pk_mul_f32 v[106:107], v[106:107], v[98:99]
	v_pk_mul_f32 v[108:109], v[108:109], v[100:101]
	v_pk_mul_f32 v[110:111], v[110:111], v[164:165] op_sel_hi:[1,0]
	v_pk_mul_f32 v[112:113], v[112:113], v[164:165] op_sel_hi:[1,0]
	v_pk_mul_f32 v[106:107], v[106:107], v[164:165] op_sel_hi:[1,0]
	v_pk_mul_f32 v[108:109], v[108:109], v[164:165] op_sel_hi:[1,0]
	v_pk_mul_f32 v[110:111], v[110:111], v[156:157]
	v_pk_mul_f32 v[112:113], v[112:113], v[158:159]
	v_pk_mul_f32 v[106:107], v[106:107], v[160:161]
	v_pk_mul_f32 v[108:109], v[108:109], v[162:163]
	v_cvt_pk_bf16_f32 v130, v110, v111
	v_cvt_pk_bf16_f32 v131, v112, v113
	v_cvt_pk_bf16_f32 v132, v106, v107
	v_cvt_pk_bf16_f32 v133, v108, v109
	v_mul_lo_u32 v142, s67, v139
	v_mad_u64_u32 v[140:141], s[50:51], s66, v139, 0
	v_add3_u32 v141, v141, v138, v142
	v_lshl_add_u64 v[140:141], v[140:141], 1, s[68:69]
	v_lshl_add_u64 v[140:141], v[140:141], 0, v[134:135]
	flat_store_dwordx4 v[140:141], v[130:133]
	flat_load_dword v130, v[136:137] offset:128
	v_or_b32_e32 v139, 32, v224
	s_waitcnt vmcnt(0) lgkmcnt(0)
; __device__ __forceinline__ unsigned cvt_pk_bf16(float lo, float hi) { f32x2 v = {lo, hi}; bf16x2_t b = __builtin_convertvector(v, bf16x2_t); return __builtin_bit_cast(unsigned, b); }
; __device__ __forceinline__ float ssq_rs(const ssq_t* p, float inv_k) { return __builtin_amdgcn_rsqf((float)(*p) * (inv_k * SSQ_INV) + RMS_EPS); }
;     __device__ __forceinline__ void operator()(const f32x4 (&acc)[2][2][4][2], const Unit& u, int wr, int wc, int fr, int fq) const {
;     ...
;         for (int ai = 0; ai < 2; ++ai)
; #pragma unroll
;             for (int m = 0; m < 4; ++m) {
;                 const int row = row0 + ai * HALF + m * 16;
;                 const float rs = ssq_rs(ss + row, inv_k);
;                 float hv[8];
; #pragma unroll
;                 for (int j = 0; j < 8; ++j) {
;                     const float gt = acc[ai][0][m][j >> 2][j & 3] * rs, up = acc[ai][1][m][j >> 2][j & 3] * rs;
;                     hv[j] = gt * __builtin_amdgcn_rcpf(1.f + __builtin_amdgcn_exp2f(-1.4426950408889634f * gt)) * up;
;                 }
;                 u32x4 w; w.x = cvt_pk_bf16(hv[0], hv[1]); w.y = cvt_pk_bf16(hv[2], hv[3]); w.z = cvt_pk_bf16(hv[4], hv[5]); w.w = cvt_pk_bf16(hv[6], hv[7]);
;                 *(u32x4*)(O + (size_t)row * ldc + col0) = w;
;             }
	v_cvt_f32_u32_e32 v130, v130
	v_fmaak_f32 v130, v250, v130, 0x358637bd
	v_rsq_f32_e32 v130, v130
	s_nop 0
	v_mul_f32_e32 v164, v130, v130
	v_mul_f32_e32 v131, 0xbfb8aa3b, v130
	v_mul_f32_e32 v156, v131, v94
	v_mul_f32_e32 v157, v131, v95
	v_mul_f32_e32 v158, v131, v96
	v_mul_f32_e32 v159, v131, v97
	v_mul_f32_e32 v160, v131, v90
	v_mul_f32_e32 v161, v131, v91
	v_mul_f32_e32 v162, v131, v92
	v_mul_f32_e32 v163, v131, v93
	v_exp_f32_e32 v156, v156
	v_exp_f32_e32 v157, v157
	v_exp_f32_e32 v158, v158
	v_exp_f32_e32 v159, v159
	v_exp_f32_e32 v160, v160
	v_exp_f32_e32 v161, v161
	v_exp_f32_e32 v162, v162
	v_exp_f32_e32 v163, v163
	v_add_f32_e32 v156, 1.0, v156
	v_add_f32_e32 v157, 1.0, v157
	v_add_f32_e32 v158, 1.0, v158
	v_add_f32_e32 v159, 1.0, v159
	v_add_f32_e32 v160, 1.0, v160
	v_add_f32_e32 v161, 1.0, v161
	v_add_f32_e32 v162, 1.0, v162
	v_add_f32_e32 v163, 1.0, v163
	v_rcp_f32_e32 v156, v156
	v_rcp_f32_e32 v157, v157
	v_rcp_f32_e32 v158, v158
	v_rcp_f32_e32 v159, v159
	v_rcp_f32_e32 v160, v160
	v_rcp_f32_e32 v161, v161
	v_rcp_f32_e32 v162, v162
	v_rcp_f32_e32 v163, v163
	v_pk_mul_f32 v[94:95], v[94:95], v[86:87]
	v_pk_mul_f32 v[96:97], v[96:97], v[88:89]
	v_pk_mul_f32 v[90:91], v[90:91], v[82:83]
	v_pk_mul_f32 v[92:93], v[92:93], v[84:85]
	v_pk_mul_f32 v[94:95], v[94:95], v[164:165] op_sel_hi:[1,0]
	v_pk_mul_f32 v[96:97], v[96:97], v[164:165] op_sel_hi:[1,0]
	v_pk_mul_f32 v[90:91], v[90:91], v[164:165] op_sel_hi:[1,0]
	v_pk_mul_f32 v[92:93], v[92:93], v[164:165] op_sel_hi:[1,0]
	v_pk_mul_f32 v[94:95], v[94:95], v[156:157]
	v_pk_mul_f32 v[96:97], v[96:97], v[158:159]
	v_pk_mul_f32 v[90:91], v[90:91], v[160:161]
	v_pk_mul_f32 v[92:93], v[92:93], v[162:163]
	v_cvt_pk_bf16_f32 v130, v94, v95
	v_cvt_pk_bf16_f32 v131, v96, v97
	v_cvt_pk_bf16_f32 v132, v90, v91
	v_cvt_pk_bf16_f32 v133, v92, v93
	v_mul_lo_u32 v142, s67, v139
	v_mad_u64_u32 v[140:141], s[50:51], s66, v139, 0
	v_add3_u32 v141, v141, v138, v142
	v_lshl_add_u64 v[140:141], v[140:141], 1, s[68:69]
	v_lshl_add_u64 v[140:141], v[140:141], 0, v[134:135]
	flat_store_dwordx4 v[140:141], v[130:133]
	flat_load_dword v130, v[136:137] offset:192
	v_or_b32_e32 v139, 48, v224
	s_waitcnt vmcnt(0) lgkmcnt(0)
	v_cvt_f32_u32_e32 v130, v130
	v_fmaak_f32 v130, v250, v130, 0x358637bd
	v_rsq_f32_e32 v130, v130
	s_nop 0
	v_mul_f32_e32 v164, v130, v130
	v_mul_f32_e32 v131, 0xbfb8aa3b, v130
	v_mul_f32_e32 v156, v131, v78
	v_mul_f32_e32 v157, v131, v79
	v_mul_f32_e32 v158, v131, v80
	v_mul_f32_e32 v159, v131, v81
	v_mul_f32_e32 v160, v131, v74
	v_mul_f32_e32 v161, v131, v75
	v_mul_f32_e32 v162, v131, v76
	v_mul_f32_e32 v163, v131, v77
	v_exp_f32_e32 v156, v156
	v_exp_f32_e32 v157, v157
	v_exp_f32_e32 v158, v158
	v_exp_f32_e32 v159, v159
	v_exp_f32_e32 v160, v160
	v_exp_f32_e32 v161, v161
	v_exp_f32_e32 v162, v162
	v_exp_f32_e32 v163, v163
	v_add_f32_e32 v156, 1.0, v156
	v_add_f32_e32 v157, 1.0, v157
	v_add_f32_e32 v158, 1.0, v158
	v_add_f32_e32 v159, 1.0, v159
	v_add_f32_e32 v160, 1.0, v160
	v_add_f32_e32 v161, 1.0, v161
	v_add_f32_e32 v162, 1.0, v162
	v_add_f32_e32 v163, 1.0, v163
	v_rcp_f32_e32 v156, v156
	v_rcp_f32_e32 v157, v157
	v_rcp_f32_e32 v158, v158
	v_rcp_f32_e32 v159, v159
	v_rcp_f32_e32 v160, v160
	v_rcp_f32_e32 v161, v161
	v_rcp_f32_e32 v162, v162
	v_rcp_f32_e32 v163, v163
	v_pk_mul_f32 v[78:79], v[78:79], v[70:71]
	v_pk_mul_f32 v[80:81], v[80:81], v[72:73]
	v_pk_mul_f32 v[74:75], v[74:75], v[66:67]
	v_pk_mul_f32 v[76:77], v[76:77], v[68:69]
	v_pk_mul_f32 v[78:79], v[78:79], v[164:165] op_sel_hi:[1,0]
	v_pk_mul_f32 v[80:81], v[80:81], v[164:165] op_sel_hi:[1,0]
	v_pk_mul_f32 v[74:75], v[74:75], v[164:165] op_sel_hi:[1,0]
	v_pk_mul_f32 v[76:77], v[76:77], v[164:165] op_sel_hi:[1,0]
	v_pk_mul_f32 v[78:79], v[78:79], v[156:157]
	v_pk_mul_f32 v[80:81], v[80:81], v[158:159]
	v_pk_mul_f32 v[74:75], v[74:75], v[160:161]
	v_pk_mul_f32 v[76:77], v[76:77], v[162:163]
	v_cvt_pk_bf16_f32 v130, v78, v79
	v_cvt_pk_bf16_f32 v131, v80, v81
	v_cvt_pk_bf16_f32 v132, v74, v75
	v_cvt_pk_bf16_f32 v133, v76, v77
	v_mul_lo_u32 v142, s67, v139
	v_mad_u64_u32 v[140:141], s[50:51], s66, v139, 0
	v_add3_u32 v141, v141, v138, v142
	v_lshl_add_u64 v[138:139], v[140:141], 1, s[68:69]
	v_lshl_add_u64 v[138:139], v[138:139], 0, v[134:135]
	flat_store_dwordx4 v[138:139], v[130:133]
	flat_load_dword v130, v[136:137] offset:512
	v_add_u32_e32 v146, 0x80, v224
	v_ashrrev_i32_e32 v147, 31, v146
	s_waitcnt vmcnt(0) lgkmcnt(0)
	v_cvt_f32_u32_e32 v130, v130
	v_fmaak_f32 v130, v250, v130, 0x358637bd
	v_rsq_f32_e32 v130, v130
	s_nop 0
	v_mul_f32_e32 v164, v130, v130
	v_mul_f32_e32 v131, 0xbfb8aa3b, v130
	v_mul_f32_e32 v156, v131, v62
	v_mul_f32_e32 v157, v131, v63
	v_mul_f32_e32 v158, v131, v64
	v_mul_f32_e32 v159, v131, v65
	v_mul_f32_e32 v160, v131, v58
	v_mul_f32_e32 v161, v131, v59
	v_mul_f32_e32 v162, v131, v60
	v_mul_f32_e32 v163, v131, v61
	v_exp_f32_e32 v156, v156
	v_exp_f32_e32 v157, v157
	v_exp_f32_e32 v158, v158
	v_exp_f32_e32 v159, v159
	v_exp_f32_e32 v160, v160
	v_exp_f32_e32 v161, v161
	v_exp_f32_e32 v162, v162
	v_exp_f32_e32 v163, v163
	v_add_f32_e32 v156, 1.0, v156
	v_add_f32_e32 v157, 1.0, v157
	v_add_f32_e32 v158, 1.0, v158
	v_add_f32_e32 v159, 1.0, v159
	v_add_f32_e32 v160, 1.0, v160
	v_add_f32_e32 v161, 1.0, v161
	v_add_f32_e32 v162, 1.0, v162
	v_add_f32_e32 v163, 1.0, v163
	v_rcp_f32_e32 v156, v156
	v_rcp_f32_e32 v157, v157
	v_rcp_f32_e32 v158, v158
	v_rcp_f32_e32 v159, v159
	v_rcp_f32_e32 v160, v160
	v_rcp_f32_e32 v161, v161
	v_rcp_f32_e32 v162, v162
	v_rcp_f32_e32 v163, v163
	v_pk_mul_f32 v[62:63], v[62:63], v[54:55]
	v_pk_mul_f32 v[64:65], v[64:65], v[56:57]
	v_pk_mul_f32 v[58:59], v[58:59], v[50:51]
	v_pk_mul_f32 v[60:61], v[60:61], v[52:53]
	v_pk_mul_f32 v[62:63], v[62:63], v[164:165] op_sel_hi:[1,0]
	v_pk_mul_f32 v[64:65], v[64:65], v[164:165] op_sel_hi:[1,0]
	v_pk_mul_f32 v[58:59], v[58:59], v[164:165] op_sel_hi:[1,0]
	v_pk_mul_f32 v[60:61], v[60:61], v[164:165] op_sel_hi:[1,0]
	v_pk_mul_f32 v[62:63], v[62:63], v[156:157]
	v_pk_mul_f32 v[64:65], v[64:65], v[158:159]
	v_pk_mul_f32 v[58:59], v[58:59], v[160:161]
	v_pk_mul_f32 v[60:61], v[60:61], v[162:163]
	v_cvt_pk_bf16_f32 v130, v62, v63
	v_cvt_pk_bf16_f32 v131, v64, v65
	v_cvt_pk_bf16_f32 v132, v58, v59
	v_cvt_pk_bf16_f32 v133, v60, v61
	v_mul_lo_u32 v140, s66, v147
	v_mul_lo_u32 v141, s67, v146
	v_mad_u64_u32 v[138:139], s[50:51], s66, v146, 0
	v_add3_u32 v139, v139, v140, v141
	v_lshl_add_u64 v[138:139], v[138:139], 1, s[68:69]
	v_lshl_add_u64 v[138:139], v[138:139], 0, v[134:135]
	flat_store_dwordx4 v[138:139], v[130:133]
	flat_load_dword v130, v[136:137] offset:576
	v_add_u32_e32 v146, 0x90, v224
	v_ashrrev_i32_e32 v147, 31, v146
	s_waitcnt vmcnt(0) lgkmcnt(0)
; __device__ __forceinline__ unsigned cvt_pk_bf16(float lo, float hi) { f32x2 v = {lo, hi}; bf16x2_t b = __builtin_convertvector(v, bf16x2_t); return __builtin_bit_cast(unsigned, b); }
; __device__ __forceinline__ float ssq_rs(const ssq_t* p, float inv_k) { return __builtin_amdgcn_rsqf((float)(*p) * (inv_k * SSQ_INV) + RMS_EPS); }
;     __device__ __forceinline__ void operator()(const f32x4 (&acc)[2][2][4][2], const Unit& u, int wr, int wc, int fr, int fq) const {
;     ...
;         for (int ai = 0; ai < 2; ++ai)
; #pragma unroll
;             for (int m = 0; m < 4; ++m) {
;                 const int row = row0 + ai * HALF + m * 16;
;                 const float rs = ssq_rs(ss + row, inv_k);
;                 float hv[8];
; #pragma unroll
;                 for (int j = 0; j < 8; ++j) {
;                     const float gt = acc[ai][0][m][j >> 2][j & 3] * rs, up = acc[ai][1][m][j >> 2][j & 3] * rs;
;                     hv[j] = gt * __builtin_amdgcn_rcpf(1.f + __builtin_amdgcn_exp2f(-1.4426950408889634f * gt)) * up;
;                 }
;                 u32x4 w; w.x = cvt_pk_bf16(hv[0], hv[1]); w.y = cvt_pk_bf16(hv[2], hv[3]); w.z = cvt_pk_bf16(hv[4], hv[5]); w.w = cvt_pk_bf16(hv[6], hv[7]);
;                 *(u32x4*)(O + (size_t)row * ldc + col0) = w;
;             }
	v_cvt_f32_u32_e32 v130, v130
	v_fmaak_f32 v130, v250, v130, 0x358637bd
	v_rsq_f32_e32 v130, v130
	s_nop 0
	v_mul_f32_e32 v164, v130, v130
	v_mul_f32_e32 v131, 0xbfb8aa3b, v130
	v_mul_f32_e32 v156, v131, v46
	v_mul_f32_e32 v157, v131, v47
	v_mul_f32_e32 v158, v131, v48
	v_mul_f32_e32 v159, v131, v49
	v_mul_f32_e32 v160, v131, v42
	v_mul_f32_e32 v161, v131, v43
	v_mul_f32_e32 v162, v131, v44
	v_mul_f32_e32 v163, v131, v45
	v_exp_f32_e32 v156, v156
	v_exp_f32_e32 v157, v157
	v_exp_f32_e32 v158, v158
	v_exp_f32_e32 v159, v159
	v_exp_f32_e32 v160, v160
	v_exp_f32_e32 v161, v161
	v_exp_f32_e32 v162, v162
	v_exp_f32_e32 v163, v163
	v_add_f32_e32 v156, 1.0, v156
	v_add_f32_e32 v157, 1.0, v157
	v_add_f32_e32 v158, 1.0, v158
	v_add_f32_e32 v159, 1.0, v159
	v_add_f32_e32 v160, 1.0, v160
	v_add_f32_e32 v161, 1.0, v161
	v_add_f32_e32 v162, 1.0, v162
	v_add_f32_e32 v163, 1.0, v163
	v_rcp_f32_e32 v156, v156
	v_rcp_f32_e32 v157, v157
	v_rcp_f32_e32 v158, v158
	v_rcp_f32_e32 v159, v159
	v_rcp_f32_e32 v160, v160
	v_rcp_f32_e32 v161, v161
	v_rcp_f32_e32 v162, v162
	v_rcp_f32_e32 v163, v163
	v_pk_mul_f32 v[46:47], v[46:47], v[38:39]
	v_pk_mul_f32 v[48:49], v[48:49], v[40:41]
	v_pk_mul_f32 v[42:43], v[42:43], v[34:35]
	v_pk_mul_f32 v[44:45], v[44:45], v[36:37]
	v_pk_mul_f32 v[46:47], v[46:47], v[164:165] op_sel_hi:[1,0]
	v_pk_mul_f32 v[48:49], v[48:49], v[164:165] op_sel_hi:[1,0]
	v_pk_mul_f32 v[42:43], v[42:43], v[164:165] op_sel_hi:[1,0]
	v_pk_mul_f32 v[44:45], v[44:45], v[164:165] op_sel_hi:[1,0]
	v_pk_mul_f32 v[46:47], v[46:47], v[156:157]
	v_pk_mul_f32 v[48:49], v[48:49], v[158:159]
	v_pk_mul_f32 v[42:43], v[42:43], v[160:161]
	v_pk_mul_f32 v[44:45], v[44:45], v[162:163]
	v_cvt_pk_bf16_f32 v130, v46, v47
	v_cvt_pk_bf16_f32 v131, v48, v49
	v_cvt_pk_bf16_f32 v132, v42, v43
	v_cvt_pk_bf16_f32 v133, v44, v45
	v_mul_lo_u32 v140, s66, v147
	v_mul_lo_u32 v141, s67, v146
	v_mad_u64_u32 v[138:139], s[50:51], s66, v146, 0
	v_add3_u32 v139, v139, v140, v141
	v_lshl_add_u64 v[138:139], v[138:139], 1, s[68:69]
	v_lshl_add_u64 v[138:139], v[138:139], 0, v[134:135]
	flat_store_dwordx4 v[138:139], v[130:133]
	flat_load_dword v130, v[136:137] offset:640
	v_add_u32_e32 v146, 0xa0, v224
	v_ashrrev_i32_e32 v147, 31, v146
	s_waitcnt vmcnt(0) lgkmcnt(0)
	v_cvt_f32_u32_e32 v130, v130
	v_fmaak_f32 v130, v250, v130, 0x358637bd
	v_rsq_f32_e32 v130, v130
	s_nop 0
	v_mul_f32_e32 v164, v130, v130
	v_mul_f32_e32 v131, 0xbfb8aa3b, v130
	v_mul_f32_e32 v156, v131, v30
	v_mul_f32_e32 v157, v131, v31
	v_mul_f32_e32 v158, v131, v32
	v_mul_f32_e32 v159, v131, v33
	v_mul_f32_e32 v160, v131, v26
	v_mul_f32_e32 v161, v131, v27
	v_mul_f32_e32 v162, v131, v28
	v_mul_f32_e32 v163, v131, v29
	v_exp_f32_e32 v156, v156
	v_exp_f32_e32 v157, v157
	v_exp_f32_e32 v158, v158
	v_exp_f32_e32 v159, v159
	v_exp_f32_e32 v160, v160
	v_exp_f32_e32 v161, v161
	v_exp_f32_e32 v162, v162
	v_exp_f32_e32 v163, v163
	v_add_f32_e32 v156, 1.0, v156
	v_add_f32_e32 v157, 1.0, v157
	v_add_f32_e32 v158, 1.0, v158
	v_add_f32_e32 v159, 1.0, v159
	v_add_f32_e32 v160, 1.0, v160
	v_add_f32_e32 v161, 1.0, v161
	v_add_f32_e32 v162, 1.0, v162
	v_add_f32_e32 v163, 1.0, v163
	v_rcp_f32_e32 v156, v156
	v_rcp_f32_e32 v157, v157
	v_rcp_f32_e32 v158, v158
	v_rcp_f32_e32 v159, v159
	v_rcp_f32_e32 v160, v160
	v_rcp_f32_e32 v161, v161
	v_rcp_f32_e32 v162, v162
	v_rcp_f32_e32 v163, v163
	v_pk_mul_f32 v[30:31], v[30:31], v[22:23]
	v_pk_mul_f32 v[32:33], v[32:33], v[24:25]
	v_pk_mul_f32 v[26:27], v[26:27], v[18:19]
	v_pk_mul_f32 v[28:29], v[28:29], v[20:21]
	v_pk_mul_f32 v[30:31], v[30:31], v[164:165] op_sel_hi:[1,0]
	v_pk_mul_f32 v[32:33], v[32:33], v[164:165] op_sel_hi:[1,0]
	v_pk_mul_f32 v[26:27], v[26:27], v[164:165] op_sel_hi:[1,0]
	v_pk_mul_f32 v[28:29], v[28:29], v[164:165] op_sel_hi:[1,0]
	v_pk_mul_f32 v[30:31], v[30:31], v[156:157]
	v_pk_mul_f32 v[32:33], v[32:33], v[158:159]
	v_pk_mul_f32 v[26:27], v[26:27], v[160:161]
	v_pk_mul_f32 v[28:29], v[28:29], v[162:163]
	v_cvt_pk_bf16_f32 v130, v30, v31
	v_cvt_pk_bf16_f32 v131, v32, v33
	v_cvt_pk_bf16_f32 v132, v26, v27
	v_cvt_pk_bf16_f32 v133, v28, v29
	v_mul_lo_u32 v140, s66, v147
	v_mul_lo_u32 v141, s67, v146
	v_mad_u64_u32 v[138:139], s[50:51], s66, v146, 0
	v_add3_u32 v139, v139, v140, v141
	v_lshl_add_u64 v[138:139], v[138:139], 1, s[68:69]
	v_lshl_add_u64 v[138:139], v[138:139], 0, v[134:135]
	flat_store_dwordx4 v[138:139], v[130:133]
	flat_load_dword v130, v[136:137] offset:704
	v_add_u32_e32 v144, 0xb0, v224
	v_ashrrev_i32_e32 v145, 31, v144
	s_waitcnt vmcnt(0) lgkmcnt(0)
	v_cvt_f32_u32_e32 v130, v130
	v_fmaak_f32 v130, v250, v130, 0x358637bd
	v_rsq_f32_e32 v130, v130
	s_nop 0
	v_mul_f32_e32 v164, v130, v130
	v_mul_f32_e32 v131, 0xbfb8aa3b, v130
	v_mul_f32_e32 v156, v131, v14
	v_mul_f32_e32 v157, v131, v15
	v_mul_f32_e32 v158, v131, v16
	v_mul_f32_e32 v159, v131, v17
	v_mul_f32_e32 v160, v131, v10
	v_mul_f32_e32 v161, v131, v11
	v_mul_f32_e32 v162, v131, v12
	v_mul_f32_e32 v163, v131, v13
	v_exp_f32_e32 v156, v156
	v_exp_f32_e32 v157, v157
	v_exp_f32_e32 v158, v158
	v_exp_f32_e32 v159, v159
	v_exp_f32_e32 v160, v160
	v_exp_f32_e32 v161, v161
	v_exp_f32_e32 v162, v162
	v_exp_f32_e32 v163, v163
	v_add_f32_e32 v156, 1.0, v156
	v_add_f32_e32 v157, 1.0, v157
	v_add_f32_e32 v158, 1.0, v158
	v_add_f32_e32 v159, 1.0, v159
	v_add_f32_e32 v160, 1.0, v160
	v_add_f32_e32 v161, 1.0, v161
	v_add_f32_e32 v162, 1.0, v162
	v_add_f32_e32 v163, 1.0, v163
	v_rcp_f32_e32 v156, v156
	v_rcp_f32_e32 v157, v157
	v_rcp_f32_e32 v158, v158
	v_rcp_f32_e32 v159, v159
	v_rcp_f32_e32 v160, v160
	v_rcp_f32_e32 v161, v161
	v_rcp_f32_e32 v162, v162
	v_rcp_f32_e32 v163, v163
	v_pk_mul_f32 v[14:15], v[14:15], v[6:7]
	v_pk_mul_f32 v[16:17], v[16:17], v[8:9]
	v_pk_mul_f32 v[10:11], v[10:11], v[2:3]
	v_pk_mul_f32 v[12:13], v[12:13], v[4:5]
	v_pk_mul_f32 v[14:15], v[14:15], v[164:165] op_sel_hi:[1,0]
	v_pk_mul_f32 v[16:17], v[16:17], v[164:165] op_sel_hi:[1,0]
	v_pk_mul_f32 v[10:11], v[10:11], v[164:165] op_sel_hi:[1,0]
	v_pk_mul_f32 v[12:13], v[12:13], v[164:165] op_sel_hi:[1,0]
	v_pk_mul_f32 v[14:15], v[14:15], v[156:157]
	v_pk_mul_f32 v[16:17], v[16:17], v[158:159]
	v_pk_mul_f32 v[10:11], v[10:11], v[160:161]
	v_pk_mul_f32 v[12:13], v[12:13], v[162:163]
	v_cvt_pk_bf16_f32 v130, v14, v15
	v_cvt_pk_bf16_f32 v131, v16, v17
	v_cvt_pk_bf16_f32 v132, v10, v11
	v_cvt_pk_bf16_f32 v133, v12, v13
	v_mul_lo_u32 v138, s66, v145
	v_mul_lo_u32 v139, s67, v144
	v_mad_u64_u32 v[136:137], s[50:51], s66, v144, 0
	v_add3_u32 v137, v137, v138, v139
	v_lshl_add_u64 v[136:137], v[136:137], 1, s[68:69]
	v_lshl_add_u64 v[134:135], v[136:137], 0, v[134:135]
	flat_store_dwordx4 v[134:135], v[130:133]
